# + non-leader workgroups poll the cross-XCD release word directly (skip the per-XCD release hop) at every seam
# speedup vs baseline: 1.0051x; 1.0022x over previous
; __device__ __forceinline__ unsigned xb_ld(unsigned* p)              { return __hip_atomic_load(p, __ATOMIC_RELAXED, __HIP_MEMORY_SCOPE_AGENT); }
; __device__ __forceinline__ unsigned xb_add(unsigned* p, unsigned v) { return __hip_atomic_fetch_add(p, v, __ATOMIC_RELAXED, __HIP_MEMORY_SCOPE_AGENT); }
; #define XB_SPIN(cond, bar) do { unsigned _sp = 0; while (cond) { __builtin_amdgcn_s_sleep(1); \
;     if ((++_sp & 255u) == 0u) { if (xb_ld(&(bar)[XB_TMO])) break; if (_sp > XB_SPIN_CAP) { atomicAdd(&(bar)[XB_TMO], 1u); break; } } } } while (0)
; __device__ __forceinline__ void xcd_barrier(const XcdBarrier& b) {
;     ...
;         const unsigned old = xb_add(&bar[XB_XSUB(b.x)], 1u);
;         const unsigned gen = old / nloc;
;         if (old + 1u == (gen + 1u) * nloc) {
;             __builtin_amdgcn_fence(__ATOMIC_RELEASE, "agent");
;             asm volatile("s_waitcnt vmcnt(0)" ::: "memory");
;             const unsigned og = xb_add(&bar[XB_TOP], 1u);
;             const unsigned tg = og / nx;
;             if (og + 1u == (tg + 1u) * nx) xb_add(&bar[XB_TOPGEN], 1u);
;             else XB_SPIN(xb_ld(&bar[XB_TOPGEN]) == tg, bar);
;             __builtin_amdgcn_fence(__ATOMIC_ACQUIRE, "agent");
;             xb_add(&bar[XB_XGEN(b.x)], 1u);
;             asm volatile("s_waitcnt vmcnt(0)" ::: "memory");
;         } else {
;             XB_SPIN(xb_ld(&bar[XB_XGEN(b.x)]) == gen, bar);
.LBB0_81:
	s_or_b64 exec, exec, s[10:11]
	v_cvt_f32_u32_e32 v4, v2
	s_waitcnt vmcnt(0)
	v_readfirstlane_b32 s3, v3
	v_sub_u32_e32 v3, 0, v2
	v_rcp_iflag_f32_e32 v4, v4
	v_add_u32_e32 v5, s3, v1
	v_mul_f32_e32 v4, 0x4f7ffffe, v4
	v_cvt_u32_f32_e32 v4, v4
	v_mul_lo_u32 v1, v3, v4
	v_mul_hi_u32 v1, v4, v1
	v_add_u32_e32 v1, v4, v1
	v_mul_hi_u32 v1, v5, v1
	v_mul_lo_u32 v3, v1, v2
	v_sub_u32_e32 v3, v5, v3
	v_add_u32_e32 v4, 1, v1
	v_cmp_ge_u32_e32 vcc, v3, v2
	s_nop 1
	v_cndmask_b32_e32 v1, v1, v4, vcc
	v_sub_u32_e32 v4, v3, v2
	v_cndmask_b32_e32 v3, v3, v4, vcc
	v_add_u32_e32 v4, 1, v1
	v_cmp_ge_u32_e32 vcc, v3, v2
	v_add_u32_e32 v3, 1, v5
	s_nop 0
	v_cndmask_b32_e32 v1, v1, v4, vcc
	v_mul_lo_u32 v4, v2, v1
	v_add_u32_e32 v2, v4, v2
	v_cmp_ne_u32_e32 vcc, v3, v2
	s_and_saveexec_b64 s[8:9], vcc
	s_xor_b64 s[8:9], exec, s[8:9]
	s_cbranch_execz .LBB0_95
	s_waitcnt lgkmcnt(0)
	v_mov_b32_e32 v0, 0x7500
	global_load_dword v0, v0, s[86:87] sc1
	s_add_u32 s16, s86, 0x7500
	s_addc_u32 s17, s87, 0
	s_waitcnt vmcnt(0)
	v_cmp_eq_u32_e32 vcc, v0, v1
	s_and_saveexec_b64 s[10:11], vcc
	s_cbranch_execz .LBB0_94
	s_add_u32 s14, s86, 0x4200
	s_addc_u32 s15, s87, 0
	s_mov_b32 s3, 1
	s_mov_b64 s[18:19], 0
	v_mov_b32_e32 v0, 0
	s_branch .LBB0_85

; __device__ __forceinline__ unsigned xb_ld(unsigned* p)              { return __hip_atomic_load(p, __ATOMIC_RELAXED, __HIP_MEMORY_SCOPE_AGENT); }
; __device__ __forceinline__ unsigned xb_add(unsigned* p, unsigned v) { return __hip_atomic_fetch_add(p, v, __ATOMIC_RELAXED, __HIP_MEMORY_SCOPE_AGENT); }
; #define XB_SPIN(cond, bar) do { unsigned _sp = 0; while (cond) { __builtin_amdgcn_s_sleep(1); \
;     if ((++_sp & 255u) == 0u) { if (xb_ld(&(bar)[XB_TMO])) break; if (_sp > XB_SPIN_CAP) { atomicAdd(&(bar)[XB_TMO], 1u); break; } } } } while (0)
; __device__ __forceinline__ void xcd_barrier(const XcdBarrier& b) {
;     ...
;         const unsigned old = xb_add(&bar[XB_XSUB(b.x)], 1u);
;         const unsigned gen = old / nloc;
;         if (old + 1u == (gen + 1u) * nloc) {
;             __builtin_amdgcn_fence(__ATOMIC_RELEASE, "agent");
;             asm volatile("s_waitcnt vmcnt(0)" ::: "memory");
;             const unsigned og = xb_add(&bar[XB_TOP], 1u);
;             const unsigned tg = og / nx;
;             if (og + 1u == (tg + 1u) * nx) xb_add(&bar[XB_TOPGEN], 1u);
;             else XB_SPIN(xb_ld(&bar[XB_TOPGEN]) == tg, bar);
;             __builtin_amdgcn_fence(__ATOMIC_ACQUIRE, "agent");
;             xb_add(&bar[XB_XGEN(b.x)], 1u);
;             asm volatile("s_waitcnt vmcnt(0)" ::: "memory");
;         } else {
;             XB_SPIN(xb_ld(&bar[XB_XGEN(b.x)]) == gen, bar);
.LBB0_149:
	s_or_b64 exec, exec, s[14:15]
	v_cvt_f32_u32_e32 v4, v2
	s_waitcnt vmcnt(0)
	v_readfirstlane_b32 s3, v3
	v_sub_u32_e32 v3, 0, v2
	v_rcp_iflag_f32_e32 v4, v4
	v_add_u32_e32 v5, s3, v1
	v_mul_f32_e32 v4, 0x4f7ffffe, v4
	v_cvt_u32_f32_e32 v4, v4
	v_mul_lo_u32 v1, v3, v4
	v_mul_hi_u32 v1, v4, v1
	v_add_u32_e32 v1, v4, v1
	v_mul_hi_u32 v1, v5, v1
	v_mul_lo_u32 v3, v1, v2
	v_sub_u32_e32 v3, v5, v3
	v_add_u32_e32 v4, 1, v1
	v_cmp_ge_u32_e32 vcc, v3, v2
	s_nop 1
	v_cndmask_b32_e32 v1, v1, v4, vcc
	v_sub_u32_e32 v4, v3, v2
	v_cndmask_b32_e32 v3, v3, v4, vcc
	v_add_u32_e32 v4, 1, v1
	v_cmp_ge_u32_e32 vcc, v3, v2
	v_add_u32_e32 v3, 1, v5
	s_nop 0
	v_cndmask_b32_e32 v1, v1, v4, vcc
	v_mul_lo_u32 v4, v2, v1
	v_add_u32_e32 v2, v4, v2
	v_cmp_ne_u32_e32 vcc, v3, v2
	s_and_saveexec_b64 s[12:13], vcc
	s_xor_b64 s[12:13], exec, s[12:13]
	s_cbranch_execz .LBB0_163
	s_waitcnt lgkmcnt(0)
	v_mov_b32_e32 v0, 0x7500
	global_load_dword v0, v0, s[86:87] sc1
	s_add_u32 s18, s86, 0x7500
	s_addc_u32 s19, s87, 0
	s_waitcnt vmcnt(0)
	v_cmp_eq_u32_e32 vcc, v0, v1
	s_and_saveexec_b64 s[14:15], vcc
	s_cbranch_execz .LBB0_162
	s_add_u32 s16, s86, 0x4200
	s_addc_u32 s17, s87, 0
	s_mov_b32 s3, 1
	s_mov_b64 s[20:21], 0
	v_mov_b32_e32 v0, 0
	s_branch .LBB0_153

; __device__ __forceinline__ unsigned xb_ld(unsigned* p)              { return __hip_atomic_load(p, __ATOMIC_RELAXED, __HIP_MEMORY_SCOPE_AGENT); }
; __device__ __forceinline__ unsigned xb_add(unsigned* p, unsigned v) { return __hip_atomic_fetch_add(p, v, __ATOMIC_RELAXED, __HIP_MEMORY_SCOPE_AGENT); }
; #define XB_SPIN(cond, bar) do { unsigned _sp = 0; while (cond) { __builtin_amdgcn_s_sleep(1); \
;     if ((++_sp & 255u) == 0u) { if (xb_ld(&(bar)[XB_TMO])) break; if (_sp > XB_SPIN_CAP) { atomicAdd(&(bar)[XB_TMO], 1u); break; } } } } while (0)
; __device__ __forceinline__ void xcd_barrier(const XcdBarrier& b) {
;     ...
;         const unsigned old = xb_add(&bar[XB_XSUB(b.x)], 1u);
;         const unsigned gen = old / nloc;
;         if (old + 1u == (gen + 1u) * nloc) {
;             __builtin_amdgcn_fence(__ATOMIC_RELEASE, "agent");
;             asm volatile("s_waitcnt vmcnt(0)" ::: "memory");
;             const unsigned og = xb_add(&bar[XB_TOP], 1u);
;             const unsigned tg = og / nx;
;             if (og + 1u == (tg + 1u) * nx) xb_add(&bar[XB_TOPGEN], 1u);
;             else XB_SPIN(xb_ld(&bar[XB_TOPGEN]) == tg, bar);
;             __builtin_amdgcn_fence(__ATOMIC_ACQUIRE, "agent");
;             xb_add(&bar[XB_XGEN(b.x)], 1u);
;             asm volatile("s_waitcnt vmcnt(0)" ::: "memory");
;         } else {
;             XB_SPIN(xb_ld(&bar[XB_XGEN(b.x)]) == gen, bar);
.LBB0_227:
	s_or_b64 exec, exec, s[12:13]
	v_cvt_f32_u32_e32 v4, v2
	s_waitcnt vmcnt(0)
	v_readfirstlane_b32 s3, v3
	v_sub_u32_e32 v3, 0, v2
	v_rcp_iflag_f32_e32 v4, v4
	v_add_u32_e32 v5, s3, v1
	v_mul_f32_e32 v4, 0x4f7ffffe, v4
	v_cvt_u32_f32_e32 v4, v4
	v_mul_lo_u32 v1, v3, v4
	v_mul_hi_u32 v1, v4, v1
	v_add_u32_e32 v1, v4, v1
	v_mul_hi_u32 v1, v5, v1
	v_mul_lo_u32 v3, v1, v2
	v_sub_u32_e32 v3, v5, v3
	v_add_u32_e32 v4, 1, v1
	v_cmp_ge_u32_e32 vcc, v3, v2
	s_nop 1
	v_cndmask_b32_e32 v1, v1, v4, vcc
	v_sub_u32_e32 v4, v3, v2
	v_cndmask_b32_e32 v3, v3, v4, vcc
	v_add_u32_e32 v4, 1, v1
	v_cmp_ge_u32_e32 vcc, v3, v2
	v_add_u32_e32 v3, 1, v5
	s_nop 0
	v_cndmask_b32_e32 v1, v1, v4, vcc
	v_mul_lo_u32 v4, v2, v1
	v_add_u32_e32 v2, v4, v2
	v_cmp_ne_u32_e32 vcc, v3, v2
	s_and_saveexec_b64 s[10:11], vcc
	s_xor_b64 s[10:11], exec, s[10:11]
	s_cbranch_execz .LBB0_241
	s_waitcnt lgkmcnt(0)
	v_mov_b32_e32 v0, 0x7500
	global_load_dword v0, v0, s[86:87] sc1
	s_add_u32 s16, s86, 0x7500
	s_addc_u32 s17, s87, 0
	s_waitcnt vmcnt(0)
	v_cmp_eq_u32_e32 vcc, v0, v1
	s_and_saveexec_b64 s[12:13], vcc
	s_cbranch_execz .LBB0_240
	s_add_u32 s14, s86, 0x4200
	s_addc_u32 s15, s87, 0
	s_mov_b32 s3, 1
	s_mov_b64 s[18:19], 0
	v_mov_b32_e32 v0, 0
	s_branch .LBB0_231

; __device__ __forceinline__ unsigned xb_ld(unsigned* p)              { return __hip_atomic_load(p, __ATOMIC_RELAXED, __HIP_MEMORY_SCOPE_AGENT); }
; __device__ __forceinline__ unsigned xb_add(unsigned* p, unsigned v) { return __hip_atomic_fetch_add(p, v, __ATOMIC_RELAXED, __HIP_MEMORY_SCOPE_AGENT); }
; #define XB_SPIN(cond, bar) do { unsigned _sp = 0; while (cond) { __builtin_amdgcn_s_sleep(1); \
;     if ((++_sp & 255u) == 0u) { if (xb_ld(&(bar)[XB_TMO])) break; if (_sp > XB_SPIN_CAP) { atomicAdd(&(bar)[XB_TMO], 1u); break; } } } } while (0)
; __device__ __forceinline__ void xcd_barrier(const XcdBarrier& b) {
;     ...
;         const unsigned old = xb_add(&bar[XB_XSUB(b.x)], 1u);
;         const unsigned gen = old / nloc;
;         if (old + 1u == (gen + 1u) * nloc) {
;             __builtin_amdgcn_fence(__ATOMIC_RELEASE, "agent");
;             asm volatile("s_waitcnt vmcnt(0)" ::: "memory");
;             const unsigned og = xb_add(&bar[XB_TOP], 1u);
;             const unsigned tg = og / nx;
;             if (og + 1u == (tg + 1u) * nx) xb_add(&bar[XB_TOPGEN], 1u);
;             else XB_SPIN(xb_ld(&bar[XB_TOPGEN]) == tg, bar);
;             __builtin_amdgcn_fence(__ATOMIC_ACQUIRE, "agent");
;             xb_add(&bar[XB_XGEN(b.x)], 1u);
;             asm volatile("s_waitcnt vmcnt(0)" ::: "memory");
;         } else {
;             XB_SPIN(xb_ld(&bar[XB_XGEN(b.x)]) == gen, bar);
.LBB0_499:
	s_or_b64 exec, exec, s[10:11]
	v_cvt_f32_u32_e32 v4, v2
	s_waitcnt vmcnt(0)
	v_readfirstlane_b32 s3, v3
	v_sub_u32_e32 v3, 0, v2
	v_rcp_iflag_f32_e32 v4, v4
	v_add_u32_e32 v5, s3, v1
	v_mul_f32_e32 v4, 0x4f7ffffe, v4
	v_cvt_u32_f32_e32 v4, v4
	v_mul_lo_u32 v1, v3, v4
	v_mul_hi_u32 v1, v4, v1
	v_add_u32_e32 v1, v4, v1
	v_mul_hi_u32 v1, v5, v1
	v_mul_lo_u32 v3, v1, v2
	v_sub_u32_e32 v3, v5, v3
	v_add_u32_e32 v4, 1, v1
	v_cmp_ge_u32_e32 vcc, v3, v2
	s_nop 1
	v_cndmask_b32_e32 v1, v1, v4, vcc
	v_sub_u32_e32 v4, v3, v2
	v_cndmask_b32_e32 v3, v3, v4, vcc
	v_add_u32_e32 v4, 1, v1
	v_cmp_ge_u32_e32 vcc, v3, v2
	v_add_u32_e32 v3, 1, v5
	s_nop 0
	v_cndmask_b32_e32 v1, v1, v4, vcc
	v_mul_lo_u32 v4, v2, v1
	v_add_u32_e32 v2, v4, v2
	v_cmp_ne_u32_e32 vcc, v3, v2
	s_and_saveexec_b64 s[8:9], vcc
	s_xor_b64 s[8:9], exec, s[8:9]
	s_cbranch_execz .LBB0_513
	s_waitcnt lgkmcnt(0)
	v_mov_b32_e32 v0, 0x7500
	global_load_dword v0, v0, s[86:87] sc1
	s_add_u32 s14, s86, 0x7500
	s_addc_u32 s15, s87, 0
	s_waitcnt vmcnt(0)
	v_cmp_eq_u32_e32 vcc, v0, v1
	s_and_saveexec_b64 s[10:11], vcc
	s_cbranch_execz .LBB0_512
	s_add_u32 s12, s86, 0x4200
	s_addc_u32 s13, s87, 0
	s_mov_b32 s3, 1
	s_mov_b64 s[16:17], 0
	v_mov_b32_e32 v0, 0
	s_branch .LBB0_503

; __device__ __forceinline__ unsigned xb_ld(unsigned* p)              { return __hip_atomic_load(p, __ATOMIC_RELAXED, __HIP_MEMORY_SCOPE_AGENT); }
; __device__ __forceinline__ unsigned xb_add(unsigned* p, unsigned v) { return __hip_atomic_fetch_add(p, v, __ATOMIC_RELAXED, __HIP_MEMORY_SCOPE_AGENT); }
; #define XB_SPIN(cond, bar) do { unsigned _sp = 0; while (cond) { __builtin_amdgcn_s_sleep(1); \
;     if ((++_sp & 255u) == 0u) { if (xb_ld(&(bar)[XB_TMO])) break; if (_sp > XB_SPIN_CAP) { atomicAdd(&(bar)[XB_TMO], 1u); break; } } } } while (0)
; __device__ __forceinline__ void xcd_barrier(const XcdBarrier& b) {
;     ...
;         const unsigned old = xb_add(&bar[XB_XSUB(b.x)], 1u);
;         const unsigned gen = old / nloc;
;         if (old + 1u == (gen + 1u) * nloc) {
;             __builtin_amdgcn_fence(__ATOMIC_RELEASE, "agent");
;             asm volatile("s_waitcnt vmcnt(0)" ::: "memory");
;             const unsigned og = xb_add(&bar[XB_TOP], 1u);
;             const unsigned tg = og / nx;
;             if (og + 1u == (tg + 1u) * nx) xb_add(&bar[XB_TOPGEN], 1u);
;             else XB_SPIN(xb_ld(&bar[XB_TOPGEN]) == tg, bar);
;             __builtin_amdgcn_fence(__ATOMIC_ACQUIRE, "agent");
;             xb_add(&bar[XB_XGEN(b.x)], 1u);
;             asm volatile("s_waitcnt vmcnt(0)" ::: "memory");
;         } else {
;             XB_SPIN(xb_ld(&bar[XB_XGEN(b.x)]) == gen, bar);
.LBB0_598:
	s_or_b64 exec, exec, s[10:11]
	v_cvt_f32_u32_e32 v4, v2
	s_waitcnt vmcnt(0)
	v_readfirstlane_b32 s8, v3
	v_sub_u32_e32 v3, 0, v2
	v_rcp_iflag_f32_e32 v4, v4
	v_add_u32_e32 v5, s8, v1
	v_mul_f32_e32 v4, 0x4f7ffffe, v4
	v_cvt_u32_f32_e32 v4, v4
	v_mul_lo_u32 v1, v3, v4
	v_mul_hi_u32 v1, v4, v1
	v_add_u32_e32 v1, v4, v1
	v_mul_hi_u32 v1, v5, v1
	v_mul_lo_u32 v3, v1, v2
	v_sub_u32_e32 v3, v5, v3
	v_add_u32_e32 v4, 1, v1
	v_cmp_ge_u32_e32 vcc, v3, v2
	s_nop 1
	v_cndmask_b32_e32 v1, v1, v4, vcc
	v_sub_u32_e32 v4, v3, v2
	v_cndmask_b32_e32 v3, v3, v4, vcc
	v_add_u32_e32 v4, 1, v1
	v_cmp_ge_u32_e32 vcc, v3, v2
	v_add_u32_e32 v3, 1, v5
	s_nop 0
	v_cndmask_b32_e32 v1, v1, v4, vcc
	v_mul_lo_u32 v4, v2, v1
	v_add_u32_e32 v2, v4, v2
	v_cmp_ne_u32_e32 vcc, v3, v2
	s_and_saveexec_b64 s[8:9], vcc
	s_xor_b64 s[8:9], exec, s[8:9]
	s_cbranch_execz .LBB0_612
	s_waitcnt lgkmcnt(0)
	v_mov_b32_e32 v0, 0x7500
	global_load_dword v0, v0, s[86:87] sc1
	s_add_u32 s14, s86, 0x7500
	s_addc_u32 s15, s87, 0
	s_waitcnt vmcnt(0)
	v_cmp_eq_u32_e32 vcc, v0, v1
	s_and_saveexec_b64 s[10:11], vcc
	s_cbranch_execz .LBB0_611
	s_add_u32 s12, s86, 0x4200
	s_addc_u32 s13, s87, 0
	s_mov_b32 s40, 1
	s_mov_b64 s[16:17], 0
	v_mov_b32_e32 v0, 0
	s_branch .LBB0_602
